# cross-XCD stage of the remaining grid barriers waits on the arrival counter itself (one atomic round trip less)
# baseline (speedup 1.0000x reference)
; __device__ __forceinline__ unsigned xb_ld(unsigned* p)              { return __hip_atomic_load(p, __ATOMIC_RELAXED, __HIP_MEMORY_SCOPE_AGENT); }
; __device__ __forceinline__ unsigned xb_add(unsigned* p, unsigned v) { return __hip_atomic_fetch_add(p, v, __ATOMIC_RELAXED, __HIP_MEMORY_SCOPE_AGENT); }
; #define XB_SPIN(cond, bar) do { unsigned _sp = 0; while (cond) { __builtin_amdgcn_s_sleep(1); \
;     if ((++_sp & 255u) == 0u) { if (xb_ld(&(bar)[XB_TMO])) break; if (_sp > XB_SPIN_CAP) { atomicAdd(&(bar)[XB_TMO], 1u); break; } } } } while (0)
; __device__ __forceinline__ void xcd_barrier(const XcdBarrier& b) {
;     ...
;             const unsigned og = xb_add(&bar[XB_TOP], 1u);
;             const unsigned tg = og / nx;
;             if (og + 1u == (tg + 1u) * nx) xb_add(&bar[XB_TOPGEN], 1u);
;             else XB_SPIN(xb_ld(&bar[XB_TOPGEN]) == tg, bar);
.LBB0_299:
	s_or_b64 exec, exec, s[4:5]
	s_waitcnt vmcnt(0)
	v_readfirstlane_b32 s2, v3
	v_sub_u32_e32 v4, 0, v2
	s_mov_b64 s[4:5], -1
	v_add_u32_e32 v3, s2, v0
	v_cvt_f32_u32_e32 v0, v2
	v_readlane_b32 s2, v253, 54
	v_readlane_b32 s3, v253, 55
	v_rcp_iflag_f32_e32 v0, v0
	s_nop 0
	v_mul_f32_e32 v0, 0x4f7ffffe, v0
	v_cvt_u32_f32_e32 v0, v0
	v_mul_lo_u32 v4, v4, v0
	v_mul_hi_u32 v4, v0, v4
	v_add_u32_e32 v0, v0, v4
	v_mul_hi_u32 v0, v3, v0
	v_mul_lo_u32 v4, v0, v2
	v_sub_u32_e32 v4, v3, v4
	v_cmp_ge_u32_e32 vcc, v4, v2
	v_add_u32_e32 v5, 1, v0
	v_add_u32_e32 v3, 1, v3
	v_cndmask_b32_e32 v0, v0, v5, vcc
	v_sub_u32_e32 v5, v4, v2
	v_cndmask_b32_e32 v4, v4, v5, vcc
	v_cmp_ge_u32_e32 vcc, v4, v2
	v_add_u32_e32 v4, 1, v0
	s_nop 0
	v_cndmask_b32_e32 v0, v0, v4, vcc
	v_mul_lo_u32 v4, v2, v0
	v_add_u32_e32 v2, v4, v2
	v_cmp_ne_u32_e32 vcc, v3, v2
	v_mov_b32_e32 v0, v2
	v_mov_b64_e32 v[2:3], s[2:3]
	s_and_saveexec_b64 s[2:3], vcc
	s_cbranch_execz .LBB0_311
	v_readlane_b32 s4, v253, 52
	v_readlane_b32 s5, v253, 53
	s_mov_b64 s[6:7], 0
	s_nop 3
	global_load_dword v2, v1, s[4:5] sc1
	s_waitcnt vmcnt(0)
	v_cmp_lt_u32_e32 vcc, v2, v0
	s_and_saveexec_b64 s[4:5], vcc
	s_cbranch_execz .LBB0_310
	s_mov_b32 s16, 1
	s_branch .LBB0_303

; __device__ __forceinline__ unsigned xb_ld(unsigned* p)              { return __hip_atomic_load(p, __ATOMIC_RELAXED, __HIP_MEMORY_SCOPE_AGENT); }
; #define XB_SPIN(cond, bar) do { unsigned _sp = 0; while (cond) { __builtin_amdgcn_s_sleep(1); \
;     if ((++_sp & 255u) == 0u) { if (xb_ld(&(bar)[XB_TMO])) break; if (_sp > XB_SPIN_CAP) { atomicAdd(&(bar)[XB_TMO], 1u); break; } } } } while (0)
; __device__ __forceinline__ void xcd_barrier(const XcdBarrier& b) {
;     ...
;             else XB_SPIN(xb_ld(&bar[XB_TOPGEN]) == tg, bar);
.LBB0_305:
	v_readlane_b32 s10, v253, 52
	v_readlane_b32 s11, v253, 53
	s_add_i32 s16, s16, 1
	s_mov_b64 s[12:13], -1
	s_nop 2
	global_load_dword v2, v1, s[10:11] sc1
	s_waitcnt vmcnt(0)
	v_cmp_ge_u32_e32 vcc, v2, v0
	s_orn2_b64 s[10:11], vcc, exec
	s_branch .LBB0_302

; __device__ __forceinline__ unsigned xb_ld(unsigned* p)              { return __hip_atomic_load(p, __ATOMIC_RELAXED, __HIP_MEMORY_SCOPE_AGENT); }
; __device__ __forceinline__ unsigned xb_add(unsigned* p, unsigned v) { return __hip_atomic_fetch_add(p, v, __ATOMIC_RELAXED, __HIP_MEMORY_SCOPE_AGENT); }
; #define XB_SPIN(cond, bar) do { unsigned _sp = 0; while (cond) { __builtin_amdgcn_s_sleep(1); \
;     if ((++_sp & 255u) == 0u) { if (xb_ld(&(bar)[XB_TMO])) break; if (_sp > XB_SPIN_CAP) { atomicAdd(&(bar)[XB_TMO], 1u); break; } } } } while (0)
; __device__ __forceinline__ void xcd_barrier(const XcdBarrier& b) {
;     ...
;             const unsigned og = xb_add(&bar[XB_TOP], 1u);
;             const unsigned tg = og / nx;
;             if (og + 1u == (tg + 1u) * nx) xb_add(&bar[XB_TOPGEN], 1u);
;             else XB_SPIN(xb_ld(&bar[XB_TOPGEN]) == tg, bar);
.LBB0_367:
	s_or_b64 exec, exec, s[6:7]
	s_waitcnt vmcnt(0)
	v_readfirstlane_b32 s4, v3
	v_sub_u32_e32 v4, 0, v2
	s_mov_b64 s[6:7], -1
	v_add_u32_e32 v3, s4, v0
	v_cvt_f32_u32_e32 v0, v2
	v_readlane_b32 s4, v253, 54
	v_readlane_b32 s5, v253, 55
	v_rcp_iflag_f32_e32 v0, v0
	s_nop 0
	v_mul_f32_e32 v0, 0x4f7ffffe, v0
	v_cvt_u32_f32_e32 v0, v0
	v_mul_lo_u32 v4, v4, v0
	v_mul_hi_u32 v4, v0, v4
	v_add_u32_e32 v0, v0, v4
	v_mul_hi_u32 v0, v3, v0
	v_mul_lo_u32 v4, v0, v2
	v_sub_u32_e32 v4, v3, v4
	v_cmp_ge_u32_e32 vcc, v4, v2
	v_add_u32_e32 v5, 1, v0
	v_add_u32_e32 v3, 1, v3
	v_cndmask_b32_e32 v0, v0, v5, vcc
	v_sub_u32_e32 v5, v4, v2
	v_cndmask_b32_e32 v4, v4, v5, vcc
	v_cmp_ge_u32_e32 vcc, v4, v2
	v_add_u32_e32 v4, 1, v0
	s_nop 0
	v_cndmask_b32_e32 v0, v0, v4, vcc
	v_mul_lo_u32 v4, v2, v0
	v_add_u32_e32 v2, v4, v2
	v_cmp_ne_u32_e32 vcc, v3, v2
	v_mov_b32_e32 v0, v2
	v_mov_b64_e32 v[2:3], s[4:5]
	s_and_saveexec_b64 s[4:5], vcc
	s_cbranch_execz .LBB0_379
	v_readlane_b32 s6, v253, 52
	v_readlane_b32 s7, v253, 53
	s_mov_b64 s[8:9], 0
	s_nop 3
	global_load_dword v2, v1, s[6:7] sc1
	s_waitcnt vmcnt(0)
	v_cmp_lt_u32_e32 vcc, v2, v0
	s_and_saveexec_b64 s[6:7], vcc
	s_cbranch_execz .LBB0_378
	s_mov_b32 s18, 1
	s_branch .LBB0_371

; __device__ __forceinline__ unsigned xb_ld(unsigned* p)              { return __hip_atomic_load(p, __ATOMIC_RELAXED, __HIP_MEMORY_SCOPE_AGENT); }
; #define XB_SPIN(cond, bar) do { unsigned _sp = 0; while (cond) { __builtin_amdgcn_s_sleep(1); \
;     if ((++_sp & 255u) == 0u) { if (xb_ld(&(bar)[XB_TMO])) break; if (_sp > XB_SPIN_CAP) { atomicAdd(&(bar)[XB_TMO], 1u); break; } } } } while (0)
; __device__ __forceinline__ void xcd_barrier(const XcdBarrier& b) {
;     ...
;             else XB_SPIN(xb_ld(&bar[XB_TOPGEN]) == tg, bar);
.LBB0_373:
	v_readlane_b32 s12, v253, 52
	v_readlane_b32 s13, v253, 53
	s_add_i32 s18, s18, 1
	s_mov_b64 s[14:15], -1
	s_nop 2
	global_load_dword v2, v1, s[12:13] sc1
	s_waitcnt vmcnt(0)
	v_cmp_ge_u32_e32 vcc, v2, v0
	s_orn2_b64 s[12:13], vcc, exec
	s_branch .LBB0_370
